# v33 + align barrier moved later: leading half does its rstd/bpermute (or issues its 16 residual loads) before waiting for the trailing half
# speedup vs baseline: 1.0012x; 1.0012x over previous
; __device__ __forceinline__ u32x4 pack8(f32x4 v0, f32x4 v1) { u32x4 w; w.x = cvt_pk_bf16(v0[0], v0[1]); w.y = cvt_pk_bf16(v0[2], v0[3]); w.z = cvt_pk_bf16(v1[0], v1[1]); w.w = cvt_pk_bf16(v1[2], v1[3]); return w; }
; __device__ __forceinline__ f32x2 gelu_pk(f32x2 v) {
;     const f32x2 av = __builtin_elementwise_abs(v), d = av * 0.2316418882f + 1.0f;
;     f32x2 t; t.x = __builtin_amdgcn_rcpf(d.x); t.y = __builtin_amdgcn_rcpf(d.y);
;     f32x2 q = t * 0.5307027145f + (-0.7265760135f); q = q * t + 0.7107068705f; q = q * t + (-0.142248368f); q = q * t + 0.127414796f; q = q * t;
;     const f32x2 s = (v * v) * (-0.72134752044f);
;     f32x2 e; e.x = __builtin_amdgcn_exp2f(s.x); e.y = __builtin_amdgcn_exp2f(s.y);
;     const f32x2 m = v * (q * e), r = v - m;
;     f32x2 o; o.x = v.x < 0.f ? m.x : r.x; o.y = v.y < 0.f ? m.y : r.y; return o;
; }
;     __device__ __forceinline__ void operator()(const f32x4 (&acc)[2][2][4][2], const Unit& u, int wr, int wc, int fr, int fq, const Pre& pre) const {
;         const int row0 = u.pm * BM + wr * 64 + fr, col0 = u.pn * BM + wc * 32 + 8 * fq;
;         float rs8[8]; rstd8(rs8, pre, fr);
;         const bool isv = u.pn >= 4;
; #pragma unroll
;         for (int ai = 0; ai < 2; ++ai)
; #pragma unroll
;             for (int m = 0; m < 4; ++m) { const int row = row0 + ai * HALF + m * 16; const float r = rs8[ai * 4 + m];
;                 bf16_t* rowp = O + (size_t)row * 2048 + col0; float sq = 0.f;
; #pragma unroll
;                 for (int bj = 0; bj < 2; ++bj) { f32x4 v0 = acc[ai][bj][m][0] * r, v1 = acc[ai][bj][m][1] * r;
;                     f32x2 a = gelu_pk((f32x2){v0[0], v0[1]}), b = gelu_pk((f32x2){v0[2], v0[3]}), c = gelu_pk((f32x2){v1[0], v1[1]}), d = gelu_pk((f32x2){v1[2], v1[3]});
;                     v0 = (f32x4){a.x, a.y, b.x, b.y}; v1 = (f32x4){c.x, c.y, d.x, d.y};
;                     sq += (v0[0] * v0[0] + v0[1] * v0[1]) + (v0[2] * v0[2] + v0[3] * v0[3]) + (v1[0] * v1[0] + v1[1] * v1[1]) + (v1[2] * v1[2] + v1[3] * v1[3]);
;                     *(u32x4*)(rowp + bj * HALF) = pack8(v0, v1); }
.LBB0_57:
	s_waitcnt vmcnt(8)
	v_ffbh_u32_e32 v154, v153
	v_min_u32_e32 v154, 32, v154
	v_lshlrev_b64 v[152:153], v154, v[152:153]
	v_min_u32_e32 v152, 1, v152
	v_or_b32_e32 v152, v153, v152
	v_cvt_f32_u32_e32 v152, v152
	v_sub_u32_e32 v153, 32, v154
	s_mov_b32 s8, 0x3e6d3388
	s_and_b64 vcc, exec, s[54:55]
	s_cbranch_vccz .Lalign_g1o
	s_barrier
.Lalign_g1o:
	s_cmp_gt_i32 s4, 3
	v_ldexp_f32 v152, v152, v153
	v_ffbh_u32_e32 v153, v147
	v_min_u32_e32 v153, 32, v153
	v_lshlrev_b64 v[146:147], v153, v[146:147]
	v_min_u32_e32 v146, 1, v146
	v_or_b32_e32 v146, v147, v146
	v_cvt_f32_u32_e32 v146, v146
	v_mul_f32_e32 v152, 0x33800000, v152
	v_fmamk_f32 v152, v152, 0x3a800000, v233
	v_rsq_f32_e32 v152, v152
	v_sub_u32_e32 v147, 32, v153
	v_ldexp_f32 v146, v146, v147
	v_and_b32_e32 v147, 64, v236
	v_or_b32_e32 v153, v147, v145
	v_lshlrev_b32_e32 v153, 2, v153
	ds_bpermute_b32 v168, v153, v152
	v_mul_f32_e32 v146, 0x33800000, v146
	v_fmamk_f32 v146, v146, 0x3a800000, v233
	v_rsq_f32_e32 v146, v146
	s_mov_b32 s12, 0xbf3a00e3
	s_waitcnt lgkmcnt(0)
	v_pk_mul_f32 v[124:125], v[124:125], v[168:169] op_sel_hi:[1,0]
	v_pk_mul_f32 v[170:171], v[120:121], v[168:169] op_sel_hi:[1,0]
	v_and_b32_e32 v121, 0x7fffffff, v125
	v_and_b32_e32 v120, 0x7fffffff, v124
	v_pk_fma_f32 v[120:121], v[120:121], s[8:9], 1.0 op_sel_hi:[1,0,0]
	v_lshl_or_b32 v162, s4, 8, v159
	v_rcp_f32_e32 v172, v120
	v_rcp_f32_e32 v173, v121
	s_cselect_b64 s[64:65], -1, 0
	s_cmp_lt_i32 s4, 4
	v_mov_b64_e32 v[120:121], s[12:13]
	s_mov_b32 s10, 0x3f07dc22
	v_pk_mul_f32 v[176:177], v[124:125], v[124:125]
	s_mov_b32 s4, 0xbf38aa3b
	v_pk_fma_f32 v[174:175], v[172:173], s[10:11], v[120:121] op_sel_hi:[1,0,0]
	s_mov_b32 s14, 0x3f35f0e3
	v_pk_mul_f32 v[176:177], v[176:177], s[4:5] op_sel_hi:[1,0]
	v_pk_fma_f32 v[174:175], v[172:173], v[174:175], s[14:15] op_sel_hi:[1,1,0]
	s_mov_b32 s36, 0xbe11a98e
	v_exp_f32_e32 v176, v176
	v_exp_f32_e32 v177, v177
	ds_bpermute_b32 v166, v153, v146
	ds_bpermute_b32 v164, v153, v152 offset:64
	ds_bpermute_b32 v160, v153, v146 offset:64
	ds_bpermute_b32 v158, v153, v152 offset:128
	ds_bpermute_b32 v156, v153, v146 offset:128
	ds_bpermute_b32 v154, v153, v152 offset:192
	ds_bpermute_b32 v146, v153, v146 offset:192
	v_xor_b32_e32 v152, 16, v236
	v_add_u32_e32 v153, 64, v147
	v_pk_fma_f32 v[174:175], v[172:173], v[174:175], s[36:37] op_sel_hi:[1,1,0]
	s_mov_b32 s66, 0x3e027906
	v_cmp_lt_i32_e32 vcc, v152, v153
	v_pk_fma_f32 v[174:175], v[172:173], v[174:175], s[66:67] op_sel_hi:[1,1,0]
	v_pk_mul_f32 v[126:127], v[126:127], v[168:169] op_sel_hi:[1,0]
	v_cndmask_b32_e32 v147, v236, v152, vcc
	v_xor_b32_e32 v152, 32, v236
	v_pk_mul_f32 v[172:173], v[172:173], v[174:175]
	v_cmp_lt_i32_e32 vcc, v152, v153
	v_pk_mul_f32 v[172:173], v[176:177], v[172:173]
	v_pk_mul_f32 v[174:175], v[126:127], v[126:127]
	v_cndmask_b32_e32 v152, v236, v152, vcc
	v_pk_mul_f32 v[176:177], v[124:125], v[172:173]
	v_pk_fma_f32 v[172:173], v[124:125], v[172:173], v[124:125] neg_lo:[1,0,0] neg_hi:[1,0,0]
	v_cmp_gt_f32_e32 vcc, 0, v124
	v_pk_mul_f32 v[174:175], v[174:175], s[4:5] op_sel_hi:[1,0]
	v_pk_mul_f32 v[122:123], v[122:123], v[168:169] op_sel_hi:[1,0]
	v_cndmask_b32_e32 v124, v172, v176, vcc
	v_cmp_gt_f32_e32 vcc, 0, v125
	v_and_b32_e32 v172, 0x7fffffff, v126
	v_exp_f32_e32 v174, v174
	v_cndmask_b32_e32 v125, v173, v177, vcc
	v_and_b32_e32 v173, 0x7fffffff, v127
	v_pk_fma_f32 v[172:173], v[172:173], s[8:9], 1.0 op_sel_hi:[1,0,0]
	v_exp_f32_e32 v175, v175
	v_rcp_f32_e32 v172, v172
	v_rcp_f32_e32 v173, v173
	v_cmp_gt_f32_e32 vcc, 0, v126
	v_lshlrev_b32_e32 v165, 2, v152
	v_lshlrev_b64 v[152:153], 12, v[142:143]
	v_pk_fma_f32 v[176:177], v[172:173], s[10:11], v[120:121] op_sel_hi:[1,0,0]
	v_ashrrev_i32_e32 v163, 31, v162
	v_pk_fma_f32 v[176:177], v[172:173], v[176:177], s[14:15] op_sel_hi:[1,1,0]
	v_lshl_add_u64 v[152:153], s[30:31], 0, v[152:153]
	v_pk_fma_f32 v[176:177], v[172:173], v[176:177], s[36:37] op_sel_hi:[1,1,0]
	v_lshl_add_u64 v[152:153], v[162:163], 1, v[152:153]
	v_pk_fma_f32 v[176:177], v[172:173], v[176:177], s[66:67] op_sel_hi:[1,1,0]
	v_lshlrev_b32_e32 v147, 2, v147
	v_pk_mul_f32 v[172:173], v[172:173], v[176:177]
	v_pk_mul_f32 v[176:177], v[170:171], v[170:171]
	v_pk_mul_f32 v[172:173], v[174:175], v[172:173]
	v_pk_mul_f32 v[176:177], v[176:177], s[4:5] op_sel_hi:[1,0]
	v_pk_mul_f32 v[174:175], v[126:127], v[172:173]
	v_pk_fma_f32 v[172:173], v[126:127], v[172:173], v[126:127] neg_lo:[1,0,0] neg_hi:[1,0,0]
	v_exp_f32_e32 v176, v176
	v_cndmask_b32_e32 v126, v172, v174, vcc
	v_cmp_gt_f32_e32 vcc, 0, v127
	v_and_b32_e32 v172, 0x7fffffff, v170
	v_exp_f32_e32 v177, v177
	v_cndmask_b32_e32 v127, v173, v175, vcc
	v_and_b32_e32 v173, 0x7fffffff, v171
	v_pk_fma_f32 v[172:173], v[172:173], s[8:9], 1.0 op_sel_hi:[1,0,0]
	v_cmp_gt_f32_e32 vcc, 0, v170
	v_rcp_f32_e32 v172, v172
	v_rcp_f32_e32 v173, v173
	v_readlane_b32 s76, v255, 14
	v_readlane_b32 s77, v255, 15
	v_pk_fma_f32 v[174:175], v[172:173], s[10:11], v[120:121] op_sel_hi:[1,0,0]
	s_nop 0
	v_pk_fma_f32 v[174:175], v[172:173], v[174:175], s[14:15] op_sel_hi:[1,1,0]
	s_nop 0
	v_pk_fma_f32 v[174:175], v[172:173], v[174:175], s[36:37] op_sel_hi:[1,1,0]
	s_nop 0
	v_pk_fma_f32 v[174:175], v[172:173], v[174:175], s[66:67] op_sel_hi:[1,1,0]
	s_nop 0
	v_pk_mul_f32 v[172:173], v[172:173], v[174:175]
	v_pk_mul_f32 v[174:175], v[122:123], v[122:123]
	v_pk_mul_f32 v[172:173], v[176:177], v[172:173]
	s_nop 0
	v_pk_mul_f32 v[176:177], v[170:171], v[172:173]
	v_pk_fma_f32 v[172:173], v[170:171], v[172:173], v[170:171] neg_lo:[1,0,0] neg_hi:[1,0,0]
	v_and_b32_e32 v170, 0x7fffffff, v122
	v_cndmask_b32_e32 v167, v172, v176, vcc
	v_cmp_gt_f32_e32 vcc, 0, v171
; __device__ __forceinline__ unsigned long long f2ss(float v) { return (unsigned long long)(v * 16777216.0f); }
; __device__ __forceinline__ u32x4 pack8(f32x4 v0, f32x4 v1) { u32x4 w; w.x = cvt_pk_bf16(v0[0], v0[1]); w.y = cvt_pk_bf16(v0[2], v0[3]); w.z = cvt_pk_bf16(v1[0], v1[1]); w.w = cvt_pk_bf16(v1[2], v1[3]); return w; }
; __device__ __forceinline__ f32x2 gelu_pk(f32x2 v) {
;     const f32x2 av = __builtin_elementwise_abs(v), d = av * 0.2316418882f + 1.0f;
;     f32x2 t; t.x = __builtin_amdgcn_rcpf(d.x); t.y = __builtin_amdgcn_rcpf(d.y);
;     f32x2 q = t * 0.5307027145f + (-0.7265760135f); q = q * t + 0.7107068705f; q = q * t + (-0.142248368f); q = q * t + 0.127414796f; q = q * t;
;     const f32x2 s = (v * v) * (-0.72134752044f);
;     f32x2 e; e.x = __builtin_amdgcn_exp2f(s.x); e.y = __builtin_amdgcn_exp2f(s.y);
;     const f32x2 m = v * (q * e), r = v - m;
;     f32x2 o; o.x = v.x < 0.f ? m.x : r.x; o.y = v.y < 0.f ? m.y : r.y; return o;
; }
;     __device__ __forceinline__ void operator()(const f32x4 (&acc)[2][2][4][2], const Unit& u, int wr, int wc, int fr, int fq, const Pre& pre) const {
;     ...
;                 for (int bj = 0; bj < 2; ++bj) { f32x4 v0 = acc[ai][bj][m][0] * r, v1 = acc[ai][bj][m][1] * r;
;                     f32x2 a = gelu_pk((f32x2){v0[0], v0[1]}), b = gelu_pk((f32x2){v0[2], v0[3]}), c = gelu_pk((f32x2){v1[0], v1[1]}), d = gelu_pk((f32x2){v1[2], v1[3]});
;                     v0 = (f32x4){a.x, a.y, b.x, b.y}; v1 = (f32x4){c.x, c.y, d.x, d.y};
;                     sq += (v0[0] * v0[0] + v0[1] * v0[1]) + (v0[2] * v0[2] + v0[3] * v0[3]) + (v1[0] * v1[0] + v1[1] * v1[1]) + (v1[2] * v1[2] + v1[3] * v1[3]);
;                     *(u32x4*)(rowp + bj * HALF) = pack8(v0, v1); }
;                 if (isv) { sq += __shfl_xor(sq, 16); sq += __shfl_xor(sq, 32); if (fq == 0) atomicAdd(vss + row, f2ss(sq)); } }
	v_and_b32_e32 v171, 0x7fffffff, v123
	v_pk_fma_f32 v[170:171], v[170:171], s[8:9], 1.0 op_sel_hi:[1,0,0]
	v_cndmask_b32_e32 v169, v173, v177, vcc
	v_rcp_f32_e32 v170, v170
	v_rcp_f32_e32 v171, v171
	v_cmp_gt_f32_e32 vcc, 0, v122
	v_pk_mul_f32 v[116:117], v[116:117], v[168:169] op_sel_hi:[1,0]
	v_pk_mul_f32 v[118:119], v[118:119], v[168:169] op_sel_hi:[1,0]
	v_pk_fma_f32 v[172:173], v[170:171], s[10:11], v[120:121] op_sel_hi:[1,0,0]
	v_pk_mul_f32 v[114:115], v[114:115], v[168:169] op_sel_hi:[1,0]
	v_pk_fma_f32 v[172:173], v[170:171], v[172:173], s[14:15] op_sel_hi:[1,1,0]
	s_nop 0
	v_pk_fma_f32 v[172:173], v[170:171], v[172:173], s[36:37] op_sel_hi:[1,1,0]
	s_nop 0
	v_pk_fma_f32 v[172:173], v[170:171], v[172:173], s[66:67] op_sel_hi:[1,1,0]
	s_nop 0
	v_pk_mul_f32 v[170:171], v[170:171], v[172:173]
	v_pk_mul_f32 v[172:173], v[174:175], s[4:5] op_sel_hi:[1,0]
	v_pk_mul_f32 v[174:175], v[116:117], v[116:117]
	v_exp_f32_e32 v172, v172
	v_exp_f32_e32 v173, v173
	v_pk_mul_f32 v[174:175], v[174:175], s[4:5] op_sel_hi:[1,0]
	v_pk_mul_f32 v[170:171], v[172:173], v[170:171]
	s_nop 0
	v_pk_mul_f32 v[172:173], v[122:123], v[170:171]
	v_pk_fma_f32 v[170:171], v[122:123], v[170:171], v[122:123] neg_lo:[1,0,0] neg_hi:[1,0,0]
	v_exp_f32_e32 v174, v174
	v_cndmask_b32_e32 v122, v170, v172, vcc
	v_cmp_gt_f32_e32 vcc, 0, v123
	v_cvt_pk_bf16_f32 v170, v124, v125
	v_exp_f32_e32 v175, v175
	s_nop 0
	v_cndmask_b32_e32 v123, v171, v173, vcc
	v_cvt_pk_bf16_f32 v171, v126, v127
	v_cvt_pk_bf16_f32 v172, v167, v169
	v_cvt_pk_bf16_f32 v173, v122, v123
	flat_store_dwordx4 v[152:153], v[170:173]
	v_cmp_gt_f32_e32 vcc, 0, v116
	s_nop 0
	v_pk_mul_f32 v[170:171], v[112:113], v[168:169] op_sel_hi:[1,0]
	v_and_b32_e32 v113, 0x7fffffff, v117
	v_and_b32_e32 v112, 0x7fffffff, v116
	v_pk_fma_f32 v[112:113], v[112:113], s[8:9], 1.0 op_sel_hi:[1,0,0]
	s_nop 0
	v_rcp_f32_e32 v112, v112
	v_rcp_f32_e32 v113, v113
	s_nop 0
	v_pk_fma_f32 v[172:173], v[112:113], s[10:11], v[120:121] op_sel_hi:[1,0,0]
	s_nop 0
	v_pk_fma_f32 v[172:173], v[112:113], v[172:173], s[14:15] op_sel_hi:[1,1,0]
	s_nop 0
	v_pk_fma_f32 v[172:173], v[112:113], v[172:173], s[36:37] op_sel_hi:[1,1,0]
	s_nop 0
	v_pk_fma_f32 v[172:173], v[112:113], v[172:173], s[66:67] op_sel_hi:[1,1,0]
	s_nop 0
	v_pk_mul_f32 v[112:113], v[112:113], v[172:173]
	v_pk_mul_f32 v[172:173], v[118:119], v[118:119]
	v_pk_mul_f32 v[112:113], v[174:175], v[112:113]
	v_pk_mul_f32 v[172:173], v[172:173], s[4:5] op_sel_hi:[1,0]
	v_pk_mul_f32 v[174:175], v[116:117], v[112:113]
	v_pk_fma_f32 v[112:113], v[116:117], v[112:113], v[116:117] neg_lo:[1,0,0] neg_hi:[1,0,0]
	v_and_b32_e32 v116, 0x7fffffff, v118
	v_cndmask_b32_e32 v112, v112, v174, vcc
	v_cmp_gt_f32_e32 vcc, 0, v117
	v_and_b32_e32 v117, 0x7fffffff, v119
	v_pk_fma_f32 v[116:117], v[116:117], s[8:9], 1.0 op_sel_hi:[1,0,0]
	v_cndmask_b32_e32 v113, v113, v175, vcc
	v_rcp_f32_e32 v116, v116
	v_rcp_f32_e32 v117, v117
	v_exp_f32_e32 v172, v172
	v_exp_f32_e32 v173, v173
	v_cmp_gt_f32_e32 vcc, 0, v118
	v_pk_fma_f32 v[174:175], v[116:117], s[10:11], v[120:121] op_sel_hi:[1,0,0]
	s_nop 0
	v_pk_fma_f32 v[174:175], v[116:117], v[174:175], s[14:15] op_sel_hi:[1,1,0]
	s_nop 0
	v_pk_fma_f32 v[174:175], v[116:117], v[174:175], s[36:37] op_sel_hi:[1,1,0]
	s_nop 0
	v_pk_fma_f32 v[174:175], v[116:117], v[174:175], s[66:67] op_sel_hi:[1,1,0]
	s_nop 0
	v_pk_mul_f32 v[116:117], v[116:117], v[174:175]
	v_pk_mul_f32 v[174:175], v[170:171], v[170:171]
	v_pk_mul_f32 v[116:117], v[172:173], v[116:117]
	v_pk_mul_f32 v[174:175], v[174:175], s[4:5] op_sel_hi:[1,0]
	v_pk_mul_f32 v[172:173], v[118:119], v[116:117]
	v_pk_fma_f32 v[116:117], v[118:119], v[116:117], v[118:119] neg_lo:[1,0,0] neg_hi:[1,0,0]
	v_and_b32_e32 v118, 0x7fffffff, v170
	v_cndmask_b32_e32 v116, v116, v172, vcc
	v_cmp_gt_f32_e32 vcc, 0, v119
	v_and_b32_e32 v119, 0x7fffffff, v171
	v_pk_fma_f32 v[118:119], v[118:119], s[8:9], 1.0 op_sel_hi:[1,0,0]
	v_cndmask_b32_e32 v117, v117, v173, vcc
	v_rcp_f32_e32 v118, v118
	v_rcp_f32_e32 v119, v119
	v_exp_f32_e32 v174, v174
	v_exp_f32_e32 v175, v175
	v_cmp_gt_f32_e32 vcc, 0, v170
	v_pk_fma_f32 v[172:173], v[118:119], s[10:11], v[120:121] op_sel_hi:[1,0,0]
	s_nop 0
	v_pk_fma_f32 v[172:173], v[118:119], v[172:173], s[14:15] op_sel_hi:[1,1,0]
	s_nop 0
	v_pk_fma_f32 v[172:173], v[118:119], v[172:173], s[36:37] op_sel_hi:[1,1,0]
	s_nop 0
	v_pk_fma_f32 v[172:173], v[118:119], v[172:173], s[66:67] op_sel_hi:[1,1,0]
	s_nop 0
	v_pk_mul_f32 v[118:119], v[118:119], v[172:173]
	v_pk_mul_f32 v[172:173], v[114:115], v[114:115]
	v_pk_mul_f32 v[118:119], v[174:175], v[118:119]
	s_nop 0
	v_pk_mul_f32 v[174:175], v[170:171], v[118:119]
	v_pk_fma_f32 v[118:119], v[170:171], v[118:119], v[170:171] neg_lo:[1,0,0] neg_hi:[1,0,0]
	v_and_b32_e32 v170, 0x7fffffff, v114
	v_cndmask_b32_e32 v118, v118, v174, vcc
	v_cmp_gt_f32_e32 vcc, 0, v171
	v_and_b32_e32 v171, 0x7fffffff, v115
	v_pk_fma_f32 v[170:171], v[170:171], s[8:9], 1.0 op_sel_hi:[1,0,0]
	v_cndmask_b32_e32 v119, v119, v175, vcc
	v_rcp_f32_e32 v170, v170
	v_rcp_f32_e32 v171, v171
	v_cmp_gt_f32_e32 vcc, 0, v114
	v_pk_fma_f32 v[120:121], v[170:171], s[10:11], v[120:121] op_sel_hi:[1,0,0]
	s_nop 0
	v_pk_fma_f32 v[120:121], v[170:171], v[120:121], s[14:15] op_sel_hi:[1,1,0]
	s_nop 0
	v_pk_fma_f32 v[120:121], v[170:171], v[120:121], s[36:37] op_sel_hi:[1,1,0]
	s_nop 0
	v_pk_fma_f32 v[120:121], v[170:171], v[120:121], s[66:67] op_sel_hi:[1,1,0]
	s_nop 0
	v_pk_mul_f32 v[120:121], v[170:171], v[120:121]
	v_pk_mul_f32 v[170:171], v[172:173], s[4:5] op_sel_hi:[1,0]
	s_nop 0
	v_exp_f32_e32 v170, v170
	v_exp_f32_e32 v171, v171
	s_nop 0
	v_pk_mul_f32 v[120:121], v[170:171], v[120:121]
	s_nop 0
	v_pk_mul_f32 v[170:171], v[114:115], v[120:121]
	v_pk_fma_f32 v[120:121], v[114:115], v[120:121], v[114:115] neg_lo:[1,0,0] neg_hi:[1,0,0]
	s_nop 0
	v_cndmask_b32_e32 v114, v120, v170, vcc
	v_cmp_gt_f32_e32 vcc, 0, v115
	v_cvt_pk_bf16_f32 v170, v112, v113
	s_nop 1
	v_cndmask_b32_e32 v115, v121, v171, vcc
	v_cvt_pk_bf16_f32 v171, v116, v117
	v_cvt_pk_bf16_f32 v172, v118, v119
	v_cvt_pk_bf16_f32 v173, v114, v115
	flat_store_dwordx4 v[152:153], v[170:173] offset:256
	s_cbranch_scc1 .LBB0_61
; __device__ __forceinline__ u32x4 pack8(f32x4 v0, f32x4 v1) { u32x4 w; w.x = cvt_pk_bf16(v0[0], v0[1]); w.y = cvt_pk_bf16(v0[2], v0[3]); w.z = cvt_pk_bf16(v1[0], v1[1]); w.w = cvt_pk_bf16(v1[2], v1[3]); return w; }
; __device__ __forceinline__ unsigned long long f2ss(float v) { return (unsigned long long)(v * 16777216.0f); }
;     __device__ __forceinline__ void operator()(const f32x4 (&acc)[2][2][4][2], const Unit& u, int wr, int wc, int fr, int fq, const Pre& pre) const {
;     ...
;                     sq += (v0[0] * v0[0] + v0[1] * v0[1]) + (v0[2] * v0[2] + v0[3] * v0[3]) + (v1[0] * v1[0] + v1[1] * v1[1]) + (v1[2] * v1[2] + v1[3] * v1[3]);
;                     *(u32x4*)(rowp + bj * HALF) = pack8(v0, v1); }
;                 if (isv) { sq += __shfl_xor(sq, 16); sq += __shfl_xor(sq, 32); if (fq == 0) atomicAdd(vss + row, f2ss(sq)); } }
	v_mul_f32_e32 v120, v123, v123
	v_mul_f32_e32 v113, v113, v113
	v_fmac_f32_e32 v120, v122, v122
	v_mul_f32_e32 v121, v125, v125
	v_mul_f32_e32 v122, v127, v127
	v_fmac_f32_e32 v113, v112, v112
	v_mul_f32_e32 v112, v117, v117
	v_fmac_f32_e32 v121, v124, v124
	v_fmac_f32_e32 v122, v126, v126
	v_fmac_f32_e32 v112, v116, v116
	v_add_f32_e32 v121, v121, v122
	v_mul_f32_e32 v122, v169, v169
	v_add_f32_e32 v112, v113, v112
	v_mul_f32_e32 v113, v119, v119
	v_fmac_f32_e32 v122, v167, v167
	v_mul_f32_e32 v115, v115, v115
	v_fmac_f32_e32 v113, v118, v118
	v_add_f32_e32 v121, v122, v121
	v_fmac_f32_e32 v115, v114, v114
	v_add_f32_e32 v112, v113, v112
	v_add_f32_e32 v120, v120, v121
	v_add_f32_e32 v112, v115, v112
	v_add_f32_e32 v112, v120, v112
	ds_bpermute_b32 v113, v147, v112
	s_waitcnt lgkmcnt(0)
	v_add_f32_e32 v112, v112, v113
	ds_bpermute_b32 v113, v165, v112
	s_and_saveexec_b64 s[26:27], s[40:41]
	s_cbranch_execz .LBB0_60
	s_waitcnt lgkmcnt(0)
	v_add_f32_e32 v112, v112, v113
	v_mul_f32_e32 v112, 0x4b800000, v112
	v_trunc_f32_e32 v112, v112
	v_mul_f32_e32 v113, 0x2f800000, v112
	v_floor_f32_e32 v113, v113
	v_fmac_f32_e32 v112, 0xcf800000, v113
	v_cvt_u32_f32_e32 v112, v112
	v_cvt_u32_f32_e32 v113, v113
	v_lshl_add_u64 v[114:115], v[142:143], 3, s[52:53]
	flat_atomic_add_x2 v[114:115], v[112:113]

; __device__ __forceinline__ unsigned long long f2ss(float v) { return (unsigned long long)(v * 16777216.0f); }
; __device__ __forceinline__ u32x4 pack8(f32x4 v0, f32x4 v1) { u32x4 w; w.x = cvt_pk_bf16(v0[0], v0[1]); w.y = cvt_pk_bf16(v0[2], v0[3]); w.z = cvt_pk_bf16(v1[0], v1[1]); w.w = cvt_pk_bf16(v1[2], v1[3]); return w; }
;     __device__ __forceinline__ void operator()(const f32x4 (&acc)[2][2][4][2], const Unit& u, int wr, int wc, int fr, int fq, const Pre&) const {
;         const int row0 = u.pm * BM + wr * 64 + fr, col0 = u.pn * BM + wc * 32 + 8 * fq;
;         typedef __attribute__((address_space(1))) u32x4 gu32x4;
;         u32x4 bwv[2][4][2];
; #pragma unroll
;         for (int ai = 0; ai < 2; ++ai)
; #pragma unroll
;             for (int m = 0; m < 4; ++m)
; #pragma unroll
;                 for (int bj = 0; bj < 2; ++bj) bwv[ai][m][bj] = *(const gu32x4*)(hb + (size_t)(row0 + ai * HALF + m * 16) * 1024 + col0 + bj * HALF);
; #pragma unroll
;         for (int ai = 0; ai < 2; ++ai)
; #pragma unroll
;             for (int m = 0; m < 4; ++m) { const int row = row0 + ai * HALF + m * 16; const size_t off = (size_t)row * 1024 + col0; float sq = 0.f;
; #pragma unroll
;                 for (int bj = 0; bj < 2; ++bj) { const u32x4 bw = bwv[ai][m][bj];
;                     const f32x4 b0 = (f32x4){__uint_as_float(bw.x << 16), __uint_as_float(bw.x & 0xffff0000u), __uint_as_float(bw.y << 16), __uint_as_float(bw.y & 0xffff0000u)};
;                     const f32x4 b1 = (f32x4){__uint_as_float(bw.z << 16), __uint_as_float(bw.z & 0xffff0000u), __uint_as_float(bw.w << 16), __uint_as_float(bw.w & 0xffff0000u)};
;                     const f32x4 v0 = acc[ai][bj][m][0] + b0, v1 = acc[ai][bj][m][1] + b1;
;                     *(gu32x4*)(hb + off + bj * HALF) = pack8(v0, v1);
;                     sq += (v0[0] * v0[0] + v0[1] * v0[1]) + (v0[2] * v0[2] + v0[3] * v0[3]) + (v1[0] * v1[0] + v1[1] * v1[1]) + (v1[2] * v1[2] + v1[3] * v1[3]); }
;                 sq += __shfl_xor(sq, 16); sq += __shfl_xor(sq, 32); if (fq == 0) atomicAdd(ssn + row, f2ss(sq)); }
.LBB0_115:
	v_lshl_or_b32 v210, s36, 8, v241
	v_lshl_add_u32 v226, s4, 8, v145
	v_ashrrev_i32_e32 v211, 31, v210
	v_lshlrev_b64 v[228:229], 1, v[210:211]
	v_ashrrev_i32_e32 v227, 31, v226
	v_lshl_add_u64 v[112:113], s[28:29], 0, v[228:229]
	v_lshlrev_b64 v[230:231], 11, v[226:227]
	v_lshl_add_u64 v[114:115], v[112:113], 0, v[230:231]
	global_load_dwordx4 v[244:247], v[114:115], off
	global_load_dwordx4 v[192:195], v[114:115], off offset:256
	v_or_b32_e32 v114, 16, v226
	v_ashrrev_i32_e32 v115, 31, v114
	v_lshlrev_b64 v[224:225], 11, v[114:115]
	v_lshl_add_u64 v[114:115], v[112:113], 0, v[224:225]
	global_load_dwordx4 v[188:191], v[114:115], off
	global_load_dwordx4 v[184:187], v[114:115], off offset:256
	v_or_b32_e32 v114, 32, v226
	v_ashrrev_i32_e32 v115, 31, v114
	v_lshlrev_b64 v[222:223], 11, v[114:115]
	v_lshl_add_u64 v[114:115], v[112:113], 0, v[222:223]
	global_load_dwordx4 v[180:183], v[114:115], off
	global_load_dwordx4 v[176:179], v[114:115], off offset:256
	v_or_b32_e32 v114, 48, v226
	v_ashrrev_i32_e32 v115, 31, v114
	s_mov_b64 s[4:5], 0x40000
	v_lshlrev_b64 v[220:221], 11, v[114:115]
	v_lshl_add_u64 v[218:219], v[230:231], 0, s[4:5]
	s_mov_b64 s[4:5], 0x48000
	v_lshl_add_u64 v[114:115], v[112:113], 0, v[220:221]
	v_lshl_add_u64 v[216:217], v[230:231], 0, s[4:5]
	s_mov_b64 s[4:5], 0x50000
	global_load_dwordx4 v[172:175], v[114:115], off
	global_load_dwordx4 v[164:167], v[114:115], off offset:256
	v_lshl_add_u64 v[114:115], v[112:113], 0, v[218:219]
	v_lshl_add_u64 v[214:215], v[230:231], 0, s[4:5]
	s_mov_b64 s[4:5], 0x58000
	global_load_dwordx4 v[156:159], v[114:115], off
	global_load_dwordx4 v[152:155], v[114:115], off offset:256
	v_lshl_add_u64 v[114:115], v[112:113], 0, v[216:217]
	v_lshl_add_u64 v[212:213], v[230:231], 0, s[4:5]
	global_load_dwordx4 v[140:143], v[114:115], off
	global_load_dwordx4 v[132:135], v[114:115], off offset:256
	v_lshl_add_u64 v[114:115], v[112:113], 0, v[214:215]
	v_lshl_add_u64 v[112:113], v[112:113], 0, v[212:213]
	global_load_dwordx4 v[124:127], v[114:115], off
	global_load_dwordx4 v[116:119], v[114:115], off offset:256
	global_load_dwordx4 v[120:123], v[112:113], off
	s_nop 0
	global_load_dwordx4 v[112:115], v[112:113], off offset:256
	s_and_b64 vcc, exec, s[54:55]
	s_cbranch_vccz .Lalign_g4
	s_barrier
.Lalign_g4:
	v_lshl_add_u64 v[230:231], s[28:29], 0, v[230:231]
	v_lshl_add_u64 v[228:229], v[230:231], 0, v[228:229]
	s_waitcnt vmcnt(0)
	v_lshlrev_b32_e32 v248, 16, v244
	v_and_b32_e32 v249, 0xffff0000, v244
	v_lshlrev_b32_e32 v244, 16, v245
	v_and_b32_e32 v245, 0xffff0000, v245
	v_lshlrev_b32_e32 v250, 16, v246
	v_and_b32_e32 v251, 0xffff0000, v246
	v_lshlrev_b32_e32 v246, 16, v247
	v_and_b32_e32 v247, 0xffff0000, v247
	v_pk_add_f32 v[170:171], v[170:171], v[244:245]
	v_pk_add_f32 v[168:169], v[168:169], v[248:249]
	v_pk_add_f32 v[244:245], v[162:163], v[246:247]
	v_pk_add_f32 v[246:247], v[160:161], v[250:251]
	v_cvt_pk_bf16_f32 v160, v168, v169
	v_cvt_pk_bf16_f32 v161, v170, v171
	s_nop 0
	v_cvt_pk_bf16_f32 v162, v246, v247
	v_cvt_pk_bf16_f32 v163, v244, v245
	global_store_dwordx4 v[228:229], v[160:163], off
	s_nop 1
	v_mul_f32_e32 v160, v169, v169
	v_mul_f32_e32 v161, v171, v171
	v_fmac_f32_e32 v160, v168, v168
	v_fmac_f32_e32 v161, v170, v170
	v_add_f32_e32 v160, v160, v161
	v_mul_f32_e32 v161, v247, v247
	v_fmac_f32_e32 v161, v246, v246
	v_add_f32_e32 v160, v161, v160
	v_mul_f32_e32 v161, v245, v245
	v_fmac_f32_e32 v161, v244, v244
	v_add_f32_e32 v196, v161, v160
	v_lshlrev_b32_e32 v160, 16, v192
	v_and_b32_e32 v161, 0xffff0000, v192
	v_lshlrev_b32_e32 v162, 16, v193
	v_and_b32_e32 v163, 0xffff0000, v193
	v_lshlrev_b32_e32 v168, 16, v194
	v_and_b32_e32 v169, 0xffff0000, v194
	v_lshlrev_b32_e32 v170, 16, v195
	v_and_b32_e32 v171, 0xffff0000, v195
	v_pk_add_f32 v[138:139], v[138:139], v[162:163]
	v_pk_add_f32 v[136:137], v[136:137], v[160:161]
	v_pk_add_f32 v[162:163], v[128:129], v[168:169]
	v_cvt_pk_bf16_f32 v128, v136, v137
	v_cvt_pk_bf16_f32 v129, v138, v139
	v_pk_add_f32 v[160:161], v[130:131], v[170:171]
	v_cvt_pk_bf16_f32 v130, v162, v163
	s_nop 0
	v_cvt_pk_bf16_f32 v131, v160, v161
	global_store_dwordx4 v[228:229], v[128:131], off offset:256
	s_nop 1
	v_mul_f32_e32 v128, v137, v137
	v_mul_f32_e32 v129, v139, v139
	v_fmac_f32_e32 v128, v136, v136
	v_fmac_f32_e32 v129, v138, v138
	v_add_f32_e32 v128, v128, v129
	v_mul_f32_e32 v129, v163, v163
	v_fmac_f32_e32 v129, v162, v162
	v_add_f32_e32 v128, v129, v128
	v_mul_f32_e32 v129, v161, v161
	v_fmac_f32_e32 v129, v160, v160
	v_and_b32_e32 v130, 64, v236
	v_add_f32_e32 v128, v129, v128
	v_xor_b32_e32 v129, 16, v236
	v_add_u32_e32 v131, 64, v130
	v_cmp_lt_i32_e32 vcc, v129, v131
	v_add_f32_e32 v128, v196, v128
	s_nop 0
	v_cndmask_b32_e32 v129, v236, v129, vcc
	v_lshlrev_b32_e32 v130, 2, v129
	ds_bpermute_b32 v129, v130, v128
	s_waitcnt lgkmcnt(0)
	v_add_f32_e32 v136, v128, v129
	v_xor_b32_e32 v128, 32, v236
	v_cmp_lt_i32_e32 vcc, v128, v131
	s_nop 1
	v_cndmask_b32_e32 v128, v236, v128, vcc
	v_lshlrev_b32_e32 v131, 2, v128
	ds_bpermute_b32 v137, v131, v136
	v_lshl_add_u64 v[128:129], v[226:227], 3, s[52:53]
	s_and_saveexec_b64 s[26:27], s[40:41]
	s_cbranch_execz .LBB0_117
	s_waitcnt lgkmcnt(0)
	v_add_f32_e32 v136, v136, v137
	v_mul_f32_e32 v136, 0x4b800000, v136
	v_trunc_f32_e32 v136, v136
	v_mul_f32_e32 v137, 0x2f800000, v136
	v_floor_f32_e32 v137, v137
	v_fmac_f32_e32 v136, 0xcf800000, v137
	v_cvt_u32_f32_e32 v136, v136
	v_cvt_u32_f32_e32 v137, v137
	flat_atomic_add_x2 v[128:129], v[136:137]

; __device__ __forceinline__ f32x4 silu4(f32x4 v) { return (f32x4){silu1(v[0]), silu1(v[1]), silu1(v[2]), silu1(v[3])}; }
; __device__ __forceinline__ u32x4 pack8(f32x4 v0, f32x4 v1) { u32x4 w; w.x = cvt_pk_bf16(v0[0], v0[1]); w.y = cvt_pk_bf16(v0[2], v0[3]); w.z = cvt_pk_bf16(v1[0], v1[1]); w.w = cvt_pk_bf16(v1[2], v1[3]); return w; }
;     __device__ __forceinline__ void operator()(const f32x4 (&acc)[2][2][4][2], const Unit& u, int wr, int wc, int fr, int fq, const Pre& pre) const {
;         const int row0 = u.pm * BM + wr * 64 + fr, col0 = u.pn * HALF + wc * 32 + 8 * fq;
;         float rs8[8]; rstd8(rs8, pre, fr);
; #pragma unroll
;         for (int ai = 0; ai < 2; ++ai)
; #pragma unroll
;             for (int m = 0; m < 4; ++m) { const int row = row0 + ai * HALF + m * 16; const float r = rs8[ai * 4 + m];
;                 const f32x4 g0 = silu4(acc[ai][0][m][0] * r), g1 = silu4(acc[ai][0][m][1] * r);
;                 const f32x4 v0 = g0 * (acc[ai][1][m][0] * r), v1 = g1 * (acc[ai][1][m][1] * r);
;                 *(u32x4*)(O + (size_t)row * 2816 + col0) = pack8(v0, v1); }
.LBB0_155:
	s_waitcnt vmcnt(8)
	v_ffbh_u32_e32 v143, v153
	v_min_u32_e32 v143, 32, v143
	v_lshlrev_b64 v[152:153], v143, v[152:153]
	v_min_u32_e32 v152, 1, v152
	v_or_b32_e32 v152, v153, v152
	v_cvt_f32_u32_e32 v152, v152
	v_sub_u32_e32 v143, 32, v143
	v_lshl_or_b32 v164, s4, 7, v159
	v_ashrrev_i32_e32 v165, 31, v164
	v_ldexp_f32 v143, v152, v143
	v_ffbh_u32_e32 v152, v147
	v_min_u32_e32 v152, 32, v152
	v_lshlrev_b64 v[146:147], v152, v[146:147]
	v_min_u32_e32 v146, 1, v146
	v_or_b32_e32 v146, v147, v146
	v_mul_f32_e32 v143, 0x33800000, v143
	v_cvt_f32_u32_e32 v146, v146
	v_fmamk_f32 v143, v143, 0x3a800000, v233
	v_rsq_f32_e32 v143, v143
	v_sub_u32_e32 v147, 32, v152
	v_ldexp_f32 v146, v146, v147
	v_and_or_b32 v147, v236, 64, v145
	v_lshlrev_b32_e32 v147, 2, v147
	ds_bpermute_b32 v166, v147, v143
	ds_bpermute_b32 v160, v147, v143 offset:64
	ds_bpermute_b32 v156, v147, v143 offset:128
	ds_bpermute_b32 v152, v147, v143 offset:192
	v_mul_f32_e32 v146, 0x33800000, v146
	s_waitcnt lgkmcnt(3)
	v_pk_mul_f32 v[124:125], v[124:125], v[166:167] op_sel_hi:[1,0]
	v_pk_mul_f32 v[126:127], v[126:127], v[166:167] op_sel_hi:[1,0]
	v_mul_f32_e32 v143, 0xbfb8aa3b, v124
	v_exp_f32_e32 v143, v143
	v_pk_mul_f32 v[120:121], v[120:121], v[166:167] op_sel_hi:[1,0]
	v_pk_mul_f32 v[122:123], v[122:123], v[166:167] op_sel_hi:[1,0]
	v_fmamk_f32 v146, v146, 0x3a800000, v233
	v_add_f32_e32 v143, 1.0, v143
	v_rcp_f32_e32 v168, v143
	v_mul_f32_e32 v143, 0xbfb8aa3b, v125
	v_exp_f32_e32 v143, v143
	v_rsq_f32_e32 v146, v146
	v_pk_mul_f32 v[116:117], v[116:117], v[166:167] op_sel_hi:[1,0]
	v_pk_mul_f32 v[118:119], v[118:119], v[166:167] op_sel_hi:[1,0]
	v_add_f32_e32 v143, 1.0, v143
	v_rcp_f32_e32 v169, v143
	v_mul_f32_e32 v143, 0xbfb8aa3b, v126
	v_exp_f32_e32 v143, v143
	ds_bpermute_b32 v162, v147, v146
	s_and_b64 vcc, exec, s[48:49]
	s_cbranch_vccz .Lalign_g3
	s_barrier
.Lalign_g3:
	v_pk_mul_f32 v[124:125], v[124:125], v[168:169]
	v_pk_mul_f32 v[112:113], v[112:113], v[166:167] op_sel_hi:[1,0]
	v_add_f32_e32 v143, 1.0, v143
	v_rcp_f32_e32 v170, v143
	v_mul_f32_e32 v143, 0xbfb8aa3b, v127
	v_exp_f32_e32 v143, v143
	v_pk_mul_f32 v[116:117], v[116:117], v[124:125]
	v_pk_mul_f32 v[114:115], v[114:115], v[166:167] op_sel_hi:[1,0]
	v_cvt_pk_bf16_f32 v116, v116, v117
	v_add_f32_e32 v143, 1.0, v143
	v_rcp_f32_e32 v171, v143
	v_mul_f32_e32 v143, 0xbfb8aa3b, v120
	v_exp_f32_e32 v143, v143
	s_movk_i32 s4, 0x1600
	v_pk_mul_f32 v[126:127], v[126:127], v[170:171]
	s_waitcnt lgkmcnt(0)
	v_pk_mul_f32 v[110:111], v[110:111], v[162:163] op_sel_hi:[1,0]
	v_add_f32_e32 v143, 1.0, v143
	v_rcp_f32_e32 v168, v143
	v_mul_f32_e32 v143, 0xbfb8aa3b, v121
	v_exp_f32_e32 v143, v143
	v_pk_mul_f32 v[118:119], v[118:119], v[126:127]
	v_pk_mul_f32 v[108:109], v[108:109], v[162:163] op_sel_hi:[1,0]
	v_cvt_pk_bf16_f32 v117, v118, v119
	v_add_f32_e32 v143, 1.0, v143
	v_rcp_f32_e32 v169, v143
	v_mul_f32_e32 v143, 0xbfb8aa3b, v122
	v_exp_f32_e32 v143, v143
	v_pk_mul_f32 v[106:107], v[106:107], v[162:163] op_sel_hi:[1,0]
	v_pk_mul_f32 v[120:121], v[120:121], v[168:169]
	v_pk_mul_f32 v[104:105], v[104:105], v[162:163] op_sel_hi:[1,0]
	v_add_f32_e32 v143, 1.0, v143
	v_rcp_f32_e32 v170, v143
	v_mul_f32_e32 v143, 0xbfb8aa3b, v123
	v_exp_f32_e32 v143, v143
	v_pk_mul_f32 v[112:113], v[112:113], v[120:121]
	v_pk_mul_f32 v[100:101], v[100:101], v[162:163] op_sel_hi:[1,0]
	v_cvt_pk_bf16_f32 v118, v112, v113
	v_add_f32_e32 v143, 1.0, v143
	v_rcp_f32_e32 v171, v143
	v_mov_b64_e32 v[112:113], s[30:31]
	v_mad_i64_i32 v[120:121], s[20:21], v142, s4, v[112:113]
	v_pk_mul_f32 v[122:123], v[122:123], v[170:171]
	v_pk_mul_f32 v[96:97], v[96:97], v[162:163] op_sel_hi:[1,0]
	v_pk_mul_f32 v[114:115], v[114:115], v[122:123]
	v_pk_mul_f32 v[98:99], v[98:99], v[162:163] op_sel_hi:[1,0]
	v_cvt_pk_bf16_f32 v119, v114, v115
	v_lshlrev_b64 v[114:115], 1, v[164:165]
	v_lshl_add_u64 v[120:121], v[120:121], 0, v[114:115]
	flat_store_dwordx4 v[120:121], v[116:119]
	v_or_b32_e32 v120, 16, v142
	v_pk_mul_f32 v[102:103], v[102:103], v[162:163] op_sel_hi:[1,0]
	v_mul_f32_e32 v116, 0xbfb8aa3b, v108
	v_mul_f32_e32 v117, 0xbfb8aa3b, v109
	v_mul_f32_e32 v118, 0xbfb8aa3b, v110
	v_mul_f32_e32 v119, 0xbfb8aa3b, v111
	v_exp_f32_e32 v116, v116
	v_exp_f32_e32 v117, v117
	v_exp_f32_e32 v118, v118
	v_exp_f32_e32 v119, v119
	v_add_f32_e32 v116, 1.0, v116
	v_add_f32_e32 v117, 1.0, v117
	v_add_f32_e32 v118, 1.0, v118
	v_add_f32_e32 v119, 1.0, v119
	v_rcp_f32_e32 v116, v116
	v_rcp_f32_e32 v117, v117
	v_rcp_f32_e32 v118, v118
	v_rcp_f32_e32 v119, v119
	v_pk_mul_f32 v[94:95], v[94:95], v[160:161] op_sel_hi:[1,0]
	v_pk_mul_f32 v[108:109], v[108:109], v[116:117]
	v_mul_f32_e32 v116, 0xbfb8aa3b, v104
	v_pk_mul_f32 v[110:111], v[110:111], v[118:119]
	v_mul_f32_e32 v117, 0xbfb8aa3b, v105
	v_mul_f32_e32 v118, 0xbfb8aa3b, v106
	v_mul_f32_e32 v119, 0xbfb8aa3b, v107
	v_exp_f32_e32 v116, v116
	v_exp_f32_e32 v117, v117
	v_exp_f32_e32 v118, v118
	v_exp_f32_e32 v119, v119
	v_add_f32_e32 v116, 1.0, v116
	v_add_f32_e32 v117, 1.0, v117
	v_add_f32_e32 v118, 1.0, v118
	v_add_f32_e32 v119, 1.0, v119
	v_rcp_f32_e32 v116, v116
	v_rcp_f32_e32 v117, v117
	v_rcp_f32_e32 v118, v118
	v_rcp_f32_e32 v119, v119
	v_pk_mul_f32 v[100:101], v[100:101], v[108:109]
	v_pk_mul_f32 v[104:105], v[104:105], v[116:117]
	v_pk_mul_f32 v[102:103], v[102:103], v[110:111]
	v_pk_mul_f32 v[106:107], v[106:107], v[118:119]
	v_pk_mul_f32 v[92:93], v[92:93], v[160:161] op_sel_hi:[1,0]
	v_pk_mul_f32 v[106:107], v[98:99], v[106:107]
	v_pk_mul_f32 v[98:99], v[96:97], v[104:105]
	v_cvt_pk_bf16_f32 v96, v100, v101
	v_mad_i64_i32 v[100:101], s[20:21], v120, s4, v[112:113]
	v_cvt_pk_bf16_f32 v97, v102, v103
; __device__ __forceinline__ unsigned cvt_pk_bf16(float lo, float hi) { unsigned r; asm volatile("v_cvt_pk_bf16_f32 %0, %1, %2" : "=v"(r) : "v"(lo), "v"(hi)); return r; }
; __device__ __forceinline__ float silu1(float v) { return v * __builtin_amdgcn_rcpf(1.0f + __builtin_amdgcn_exp2f(-1.4426950408889634f * v)); }
; __device__ __forceinline__ f32x4 silu4(f32x4 v) { return (f32x4){silu1(v[0]), silu1(v[1]), silu1(v[2]), silu1(v[3])}; }
; __device__ __forceinline__ u32x4 pack8(f32x4 v0, f32x4 v1) { u32x4 w; w.x = cvt_pk_bf16(v0[0], v0[1]); w.y = cvt_pk_bf16(v0[2], v0[3]); w.z = cvt_pk_bf16(v1[0], v1[1]); w.w = cvt_pk_bf16(v1[2], v1[3]); return w; }
;     __device__ __forceinline__ void operator()(const f32x4 (&acc)[2][2][4][2], const Unit& u, int wr, int wc, int fr, int fq, const Pre& pre) const {
;     ...
;             for (int m = 0; m < 4; ++m) { const int row = row0 + ai * HALF + m * 16; const float r = rs8[ai * 4 + m];
;                 const f32x4 g0 = silu4(acc[ai][0][m][0] * r), g1 = silu4(acc[ai][0][m][1] * r);
;                 const f32x4 v0 = g0 * (acc[ai][1][m][0] * r), v1 = g1 * (acc[ai][1][m][1] * r);
;                 *(u32x4*)(O + (size_t)row * 2816 + col0) = pack8(v0, v1); }
	v_cvt_pk_bf16_f32 v98, v98, v99
	v_cvt_pk_bf16_f32 v99, v106, v107
	v_lshl_add_u64 v[100:101], v[100:101], 0, v[114:115]
	flat_store_dwordx4 v[100:101], v[96:99]
	v_pk_mul_f32 v[90:91], v[90:91], v[160:161] op_sel_hi:[1,0]
	v_pk_mul_f32 v[88:89], v[88:89], v[160:161] op_sel_hi:[1,0]
	v_mul_f32_e32 v96, 0xbfb8aa3b, v92
	v_mul_f32_e32 v97, 0xbfb8aa3b, v93
	v_mul_f32_e32 v98, 0xbfb8aa3b, v94
	v_mul_f32_e32 v99, 0xbfb8aa3b, v95
	v_exp_f32_e32 v96, v96
	v_exp_f32_e32 v97, v97
	v_exp_f32_e32 v98, v98
	v_exp_f32_e32 v99, v99
	v_add_f32_e32 v96, 1.0, v96
	v_add_f32_e32 v97, 1.0, v97
	v_add_f32_e32 v98, 1.0, v98
	v_add_f32_e32 v99, 1.0, v99
	v_rcp_f32_e32 v96, v96
	v_rcp_f32_e32 v97, v97
	v_rcp_f32_e32 v98, v98
	v_rcp_f32_e32 v99, v99
	ds_bpermute_b32 v158, v147, v146 offset:64
	v_pk_mul_f32 v[92:93], v[92:93], v[96:97]
	v_mul_f32_e32 v96, 0xbfb8aa3b, v88
	v_pk_mul_f32 v[94:95], v[94:95], v[98:99]
	v_mul_f32_e32 v97, 0xbfb8aa3b, v89
	v_mul_f32_e32 v98, 0xbfb8aa3b, v90
	v_mul_f32_e32 v99, 0xbfb8aa3b, v91
	v_exp_f32_e32 v96, v96
	v_exp_f32_e32 v97, v97
	v_exp_f32_e32 v98, v98
	v_exp_f32_e32 v99, v99
	v_add_f32_e32 v96, 1.0, v96
	v_add_f32_e32 v97, 1.0, v97
	v_add_f32_e32 v98, 1.0, v98
	v_add_f32_e32 v99, 1.0, v99
	v_rcp_f32_e32 v96, v96
	v_rcp_f32_e32 v97, v97
	v_rcp_f32_e32 v98, v98
	v_rcp_f32_e32 v99, v99
	v_pk_mul_f32 v[84:85], v[84:85], v[160:161] op_sel_hi:[1,0]
	v_or_b32_e32 v100, 32, v142
	v_pk_mul_f32 v[88:89], v[88:89], v[96:97]
	v_pk_mul_f32 v[90:91], v[90:91], v[98:99]
	v_pk_mul_f32 v[84:85], v[84:85], v[92:93]
	v_pk_mul_f32 v[80:81], v[80:81], v[160:161] op_sel_hi:[1,0]
	v_pk_mul_f32 v[82:83], v[82:83], v[160:161] op_sel_hi:[1,0]
	v_pk_mul_f32 v[86:87], v[86:87], v[160:161] op_sel_hi:[1,0]
	v_pk_mul_f32 v[90:91], v[82:83], v[90:91]
	v_pk_mul_f32 v[82:83], v[80:81], v[88:89]
	v_cvt_pk_bf16_f32 v80, v84, v85
	v_mad_i64_i32 v[84:85], s[20:21], v100, s4, v[112:113]
	v_pk_mul_f32 v[86:87], v[86:87], v[94:95]
	v_lshl_add_u64 v[84:85], v[84:85], 0, v[114:115]
	v_cvt_pk_bf16_f32 v81, v86, v87
	v_cvt_pk_bf16_f32 v82, v82, v83
	v_cvt_pk_bf16_f32 v83, v90, v91
	s_waitcnt lgkmcnt(0)
	v_pk_mul_f32 v[78:79], v[78:79], v[158:159] op_sel_hi:[1,0]
	v_pk_mul_f32 v[76:77], v[76:77], v[158:159] op_sel_hi:[1,0]
	flat_store_dwordx4 v[84:85], v[80:83]
	v_pk_mul_f32 v[74:75], v[74:75], v[158:159] op_sel_hi:[1,0]
	v_pk_mul_f32 v[72:73], v[72:73], v[158:159] op_sel_hi:[1,0]
	v_mul_f32_e32 v80, 0xbfb8aa3b, v76
	v_mul_f32_e32 v81, 0xbfb8aa3b, v77
	v_mul_f32_e32 v82, 0xbfb8aa3b, v78
	v_mul_f32_e32 v83, 0xbfb8aa3b, v79
	v_exp_f32_e32 v80, v80
	v_exp_f32_e32 v81, v81
	v_exp_f32_e32 v82, v82
	v_exp_f32_e32 v83, v83
	v_add_f32_e32 v80, 1.0, v80
	v_add_f32_e32 v81, 1.0, v81
	v_add_f32_e32 v82, 1.0, v82
	v_add_f32_e32 v83, 1.0, v83
	v_rcp_f32_e32 v80, v80
	v_rcp_f32_e32 v81, v81
	v_rcp_f32_e32 v82, v82
	v_rcp_f32_e32 v83, v83
	v_pk_mul_f32 v[68:69], v[68:69], v[158:159] op_sel_hi:[1,0]
	v_pk_mul_f32 v[76:77], v[76:77], v[80:81]
	v_mul_f32_e32 v80, 0xbfb8aa3b, v72
	v_pk_mul_f32 v[78:79], v[78:79], v[82:83]
	v_mul_f32_e32 v81, 0xbfb8aa3b, v73
	v_mul_f32_e32 v82, 0xbfb8aa3b, v74
	v_mul_f32_e32 v83, 0xbfb8aa3b, v75
	v_exp_f32_e32 v80, v80
	v_exp_f32_e32 v81, v81
	v_exp_f32_e32 v82, v82
	v_exp_f32_e32 v83, v83
	v_add_f32_e32 v80, 1.0, v80
	v_add_f32_e32 v81, 1.0, v81
	v_add_f32_e32 v82, 1.0, v82
	v_add_f32_e32 v83, 1.0, v83
	v_rcp_f32_e32 v80, v80
	v_rcp_f32_e32 v81, v81
	v_rcp_f32_e32 v82, v82
	v_rcp_f32_e32 v83, v83
	v_or_b32_e32 v84, 48, v142
	v_pk_mul_f32 v[72:73], v[72:73], v[80:81]
	v_pk_mul_f32 v[68:69], v[68:69], v[76:77]
	v_pk_mul_f32 v[74:75], v[74:75], v[82:83]
	v_pk_mul_f32 v[64:65], v[64:65], v[158:159] op_sel_hi:[1,0]
	v_pk_mul_f32 v[66:67], v[66:67], v[158:159] op_sel_hi:[1,0]
	v_pk_mul_f32 v[70:71], v[70:71], v[158:159] op_sel_hi:[1,0]
	v_pk_mul_f32 v[74:75], v[66:67], v[74:75]
	v_pk_mul_f32 v[66:67], v[64:65], v[72:73]
	v_cvt_pk_bf16_f32 v64, v68, v69
	v_mad_i64_i32 v[68:69], s[20:21], v84, s4, v[112:113]
	v_pk_mul_f32 v[70:71], v[70:71], v[78:79]
	v_lshl_add_u64 v[68:69], v[68:69], 0, v[114:115]
	v_cvt_pk_bf16_f32 v65, v70, v71
	v_cvt_pk_bf16_f32 v66, v66, v67
	v_cvt_pk_bf16_f32 v67, v74, v75
	v_pk_mul_f32 v[62:63], v[62:63], v[156:157] op_sel_hi:[1,0]
	v_pk_mul_f32 v[60:61], v[60:61], v[156:157] op_sel_hi:[1,0]
	flat_store_dwordx4 v[68:69], v[64:67]
	v_pk_mul_f32 v[58:59], v[58:59], v[156:157] op_sel_hi:[1,0]
	v_pk_mul_f32 v[56:57], v[56:57], v[156:157] op_sel_hi:[1,0]
	v_mul_f32_e32 v64, 0xbfb8aa3b, v60
	v_mul_f32_e32 v65, 0xbfb8aa3b, v61
	v_mul_f32_e32 v66, 0xbfb8aa3b, v62
	v_mul_f32_e32 v67, 0xbfb8aa3b, v63
	v_exp_f32_e32 v64, v64
	v_exp_f32_e32 v65, v65
	v_exp_f32_e32 v66, v66
	v_exp_f32_e32 v67, v67
	v_add_f32_e32 v64, 1.0, v64
	v_add_f32_e32 v65, 1.0, v65
	v_add_f32_e32 v66, 1.0, v66
	v_add_f32_e32 v67, 1.0, v67
	v_rcp_f32_e32 v64, v64
	v_rcp_f32_e32 v65, v65
	v_rcp_f32_e32 v66, v66
	v_rcp_f32_e32 v67, v67
	ds_bpermute_b32 v154, v147, v146 offset:128
	v_pk_mul_f32 v[60:61], v[60:61], v[64:65]
	v_mul_f32_e32 v64, 0xbfb8aa3b, v56
	v_pk_mul_f32 v[62:63], v[62:63], v[66:67]
	v_mul_f32_e32 v65, 0xbfb8aa3b, v57
	v_mul_f32_e32 v66, 0xbfb8aa3b, v58
	v_mul_f32_e32 v67, 0xbfb8aa3b, v59
	v_exp_f32_e32 v64, v64
	v_exp_f32_e32 v65, v65
	v_exp_f32_e32 v66, v66
	v_exp_f32_e32 v67, v67
	v_add_f32_e32 v64, 1.0, v64
	v_add_f32_e32 v65, 1.0, v65
	v_add_f32_e32 v66, 1.0, v66
	v_add_f32_e32 v67, 1.0, v67
	v_rcp_f32_e32 v64, v64
	v_rcp_f32_e32 v65, v65
	v_rcp_f32_e32 v66, v66
	v_rcp_f32_e32 v67, v67
	v_pk_mul_f32 v[52:53], v[52:53], v[156:157] op_sel_hi:[1,0]
	v_add_u32_e32 v68, 0x80, v142
	v_pk_mul_f32 v[56:57], v[56:57], v[64:65]
	v_pk_mul_f32 v[58:59], v[58:59], v[66:67]
	v_pk_mul_f32 v[52:53], v[52:53], v[60:61]
	v_pk_mul_f32 v[48:49], v[48:49], v[156:157] op_sel_hi:[1,0]
	v_pk_mul_f32 v[50:51], v[50:51], v[156:157] op_sel_hi:[1,0]
	v_pk_mul_f32 v[54:55], v[54:55], v[156:157] op_sel_hi:[1,0]
	v_pk_mul_f32 v[58:59], v[50:51], v[58:59]
	v_pk_mul_f32 v[50:51], v[48:49], v[56:57]
	v_cvt_pk_bf16_f32 v48, v52, v53
	v_mad_i64_i32 v[52:53], s[20:21], v68, s4, v[112:113]
	v_pk_mul_f32 v[54:55], v[54:55], v[62:63]
	v_lshl_add_u64 v[52:53], v[52:53], 0, v[114:115]
	v_cvt_pk_bf16_f32 v49, v54, v55
	v_cvt_pk_bf16_f32 v50, v50, v51
	v_cvt_pk_bf16_f32 v51, v58, v59
	s_waitcnt lgkmcnt(0)
; __device__ __forceinline__ f32x4 silu4(f32x4 v) { return (f32x4){silu1(v[0]), silu1(v[1]), silu1(v[2]), silu1(v[3])}; }
; __device__ __forceinline__ u32x4 pack8(f32x4 v0, f32x4 v1) { u32x4 w; w.x = cvt_pk_bf16(v0[0], v0[1]); w.y = cvt_pk_bf16(v0[2], v0[3]); w.z = cvt_pk_bf16(v1[0], v1[1]); w.w = cvt_pk_bf16(v1[2], v1[3]); return w; }
; #define PG8_BAR __builtin_amdgcn_s_barrier()
;     __device__ __forceinline__ void operator()(const f32x4 (&acc)[2][2][4][2], const Unit& u, int wr, int wc, int fr, int fq, const Pre& pre) const {
;     ...
;             for (int m = 0; m < 4; ++m) { const int row = row0 + ai * HALF + m * 16; const float r = rs8[ai * 4 + m];
;                 const f32x4 g0 = silu4(acc[ai][0][m][0] * r), g1 = silu4(acc[ai][0][m][1] * r);
;                 const f32x4 v0 = g0 * (acc[ai][1][m][0] * r), v1 = g1 * (acc[ai][1][m][1] * r);
;                 *(u32x4*)(O + (size_t)row * 2816 + col0) = pack8(v0, v1); }
; template <class Epi, class Sched, bool ALIGN_EPI = false, bool SP2 = false>
; __device__ __forceinline__ void gemm_phase(PG8_LAS unsigned char* lds, const Gemm g, const Sched& S, const Epi& E) {
;     ...
;         if constexpr (!Epi::AFTER_DRAIN) { E(acc, cur, wr, wc, fr, fq, pre); S.done(cur); }
;         if (!has_next) break;
; #pragma unroll
;         for (int a = 0; a < 2; ++a)
; #pragma unroll
;             for (int b = 0; b < 2; ++b)
; #pragma unroll
;                 for (int m = 0; m < 4; ++m)
; #pragma unroll
;                     for (int n = 0; n < 2; ++n) acc[a][b][m][n] = (f32x4){0.f, 0.f, 0.f, 0.f};
;         cur = nxt; cA = nA; cB = nB; ++ui;
;         if constexpr (ALIGN_EPI) { if (wr == 1) PG8_BAR; }
	v_pk_mul_f32 v[46:47], v[46:47], v[154:155] op_sel_hi:[1,0]
	v_pk_mul_f32 v[44:45], v[44:45], v[154:155] op_sel_hi:[1,0]
	flat_store_dwordx4 v[52:53], v[48:51]
	v_pk_mul_f32 v[42:43], v[42:43], v[154:155] op_sel_hi:[1,0]
	v_pk_mul_f32 v[40:41], v[40:41], v[154:155] op_sel_hi:[1,0]
	v_mul_f32_e32 v48, 0xbfb8aa3b, v44
	v_mul_f32_e32 v49, 0xbfb8aa3b, v45
	v_mul_f32_e32 v50, 0xbfb8aa3b, v46
	v_mul_f32_e32 v51, 0xbfb8aa3b, v47
	v_exp_f32_e32 v48, v48
	v_exp_f32_e32 v49, v49
	v_exp_f32_e32 v50, v50
	v_exp_f32_e32 v51, v51
	v_add_f32_e32 v48, 1.0, v48
	v_add_f32_e32 v49, 1.0, v49
	v_add_f32_e32 v50, 1.0, v50
	v_add_f32_e32 v51, 1.0, v51
	v_rcp_f32_e32 v48, v48
	v_rcp_f32_e32 v49, v49
	v_rcp_f32_e32 v50, v50
	v_rcp_f32_e32 v51, v51
	v_pk_mul_f32 v[36:37], v[36:37], v[154:155] op_sel_hi:[1,0]
	v_pk_mul_f32 v[44:45], v[44:45], v[48:49]
	v_mul_f32_e32 v48, 0xbfb8aa3b, v40
	v_pk_mul_f32 v[46:47], v[46:47], v[50:51]
	v_mul_f32_e32 v49, 0xbfb8aa3b, v41
	v_mul_f32_e32 v50, 0xbfb8aa3b, v42
	v_mul_f32_e32 v51, 0xbfb8aa3b, v43
	v_exp_f32_e32 v48, v48
	v_exp_f32_e32 v49, v49
	v_exp_f32_e32 v50, v50
	v_exp_f32_e32 v51, v51
	v_add_f32_e32 v48, 1.0, v48
	v_add_f32_e32 v49, 1.0, v49
	v_add_f32_e32 v50, 1.0, v50
	v_add_f32_e32 v51, 1.0, v51
	v_rcp_f32_e32 v48, v48
	v_rcp_f32_e32 v49, v49
	v_rcp_f32_e32 v50, v50
	v_rcp_f32_e32 v51, v51
	v_add_u32_e32 v52, 0x90, v142
	v_pk_mul_f32 v[40:41], v[40:41], v[48:49]
	v_pk_mul_f32 v[36:37], v[36:37], v[44:45]
	v_pk_mul_f32 v[42:43], v[42:43], v[50:51]
	v_pk_mul_f32 v[32:33], v[32:33], v[154:155] op_sel_hi:[1,0]
	v_pk_mul_f32 v[34:35], v[34:35], v[154:155] op_sel_hi:[1,0]
	v_pk_mul_f32 v[38:39], v[38:39], v[154:155] op_sel_hi:[1,0]
	v_pk_mul_f32 v[42:43], v[34:35], v[42:43]
	v_pk_mul_f32 v[34:35], v[32:33], v[40:41]
	v_cvt_pk_bf16_f32 v32, v36, v37
	v_mad_i64_i32 v[36:37], s[20:21], v52, s4, v[112:113]
	v_pk_mul_f32 v[38:39], v[38:39], v[46:47]
	v_lshl_add_u64 v[36:37], v[36:37], 0, v[114:115]
	v_cvt_pk_bf16_f32 v33, v38, v39
	v_cvt_pk_bf16_f32 v34, v34, v35
	v_cvt_pk_bf16_f32 v35, v42, v43
	v_pk_mul_f32 v[30:31], v[30:31], v[152:153] op_sel_hi:[1,0]
	v_pk_mul_f32 v[28:29], v[28:29], v[152:153] op_sel_hi:[1,0]
	flat_store_dwordx4 v[36:37], v[32:35]
	v_pk_mul_f32 v[26:27], v[26:27], v[152:153] op_sel_hi:[1,0]
	v_pk_mul_f32 v[24:25], v[24:25], v[152:153] op_sel_hi:[1,0]
	v_mul_f32_e32 v32, 0xbfb8aa3b, v28
	v_mul_f32_e32 v33, 0xbfb8aa3b, v29
	v_mul_f32_e32 v34, 0xbfb8aa3b, v30
	v_mul_f32_e32 v35, 0xbfb8aa3b, v31
	v_exp_f32_e32 v32, v32
	v_exp_f32_e32 v33, v33
	v_exp_f32_e32 v34, v34
	v_exp_f32_e32 v35, v35
	v_add_f32_e32 v32, 1.0, v32
	v_add_f32_e32 v33, 1.0, v33
	v_add_f32_e32 v34, 1.0, v34
	v_add_f32_e32 v35, 1.0, v35
	v_rcp_f32_e32 v32, v32
	v_rcp_f32_e32 v33, v33
	v_rcp_f32_e32 v34, v34
	v_rcp_f32_e32 v35, v35
	ds_bpermute_b32 v146, v147, v146 offset:192
	v_pk_mul_f32 v[28:29], v[28:29], v[32:33]
	v_mul_f32_e32 v32, 0xbfb8aa3b, v24
	v_pk_mul_f32 v[30:31], v[30:31], v[34:35]
	v_mul_f32_e32 v33, 0xbfb8aa3b, v25
	v_mul_f32_e32 v34, 0xbfb8aa3b, v26
	v_mul_f32_e32 v35, 0xbfb8aa3b, v27
	v_exp_f32_e32 v32, v32
	v_exp_f32_e32 v33, v33
	v_exp_f32_e32 v34, v34
	v_exp_f32_e32 v35, v35
	v_add_f32_e32 v32, 1.0, v32
	v_add_f32_e32 v33, 1.0, v33
	v_add_f32_e32 v34, 1.0, v34
	v_add_f32_e32 v35, 1.0, v35
	v_rcp_f32_e32 v32, v32
	v_rcp_f32_e32 v33, v33
	v_rcp_f32_e32 v34, v34
	v_rcp_f32_e32 v35, v35
	v_pk_mul_f32 v[20:21], v[20:21], v[152:153] op_sel_hi:[1,0]
	v_add_u32_e32 v36, 0xa0, v142
	v_pk_mul_f32 v[24:25], v[24:25], v[32:33]
	v_pk_mul_f32 v[26:27], v[26:27], v[34:35]
	v_pk_mul_f32 v[20:21], v[20:21], v[28:29]
	v_pk_mul_f32 v[16:17], v[16:17], v[152:153] op_sel_hi:[1,0]
	v_pk_mul_f32 v[18:19], v[18:19], v[152:153] op_sel_hi:[1,0]
	v_pk_mul_f32 v[22:23], v[22:23], v[152:153] op_sel_hi:[1,0]
	v_pk_mul_f32 v[26:27], v[18:19], v[26:27]
	v_pk_mul_f32 v[18:19], v[16:17], v[24:25]
	v_cvt_pk_bf16_f32 v16, v20, v21
	v_mad_i64_i32 v[20:21], s[20:21], v36, s4, v[112:113]
	v_pk_mul_f32 v[22:23], v[22:23], v[30:31]
	v_lshl_add_u64 v[20:21], v[20:21], 0, v[114:115]
	v_cvt_pk_bf16_f32 v17, v22, v23
	v_cvt_pk_bf16_f32 v18, v18, v19
	v_cvt_pk_bf16_f32 v19, v26, v27
	s_waitcnt lgkmcnt(0)
	v_pk_mul_f32 v[14:15], v[14:15], v[146:147] op_sel_hi:[1,0]
	v_pk_mul_f32 v[12:13], v[12:13], v[146:147] op_sel_hi:[1,0]
	flat_store_dwordx4 v[20:21], v[16:19]
	v_pk_mul_f32 v[10:11], v[10:11], v[146:147] op_sel_hi:[1,0]
	v_pk_mul_f32 v[8:9], v[8:9], v[146:147] op_sel_hi:[1,0]
	v_mul_f32_e32 v16, 0xbfb8aa3b, v12
	v_mul_f32_e32 v17, 0xbfb8aa3b, v13
	v_mul_f32_e32 v18, 0xbfb8aa3b, v14
	v_mul_f32_e32 v19, 0xbfb8aa3b, v15
	v_exp_f32_e32 v16, v16
	v_exp_f32_e32 v17, v17
	v_exp_f32_e32 v18, v18
	v_exp_f32_e32 v19, v19
	v_add_f32_e32 v16, 1.0, v16
	v_add_f32_e32 v17, 1.0, v17
	v_add_f32_e32 v18, 1.0, v18
	v_add_f32_e32 v19, 1.0, v19
	v_rcp_f32_e32 v16, v16
	v_rcp_f32_e32 v17, v17
	v_rcp_f32_e32 v18, v18
	v_rcp_f32_e32 v19, v19
	v_pk_mul_f32 v[4:5], v[4:5], v[146:147] op_sel_hi:[1,0]
	v_pk_mul_f32 v[12:13], v[12:13], v[16:17]
	v_mul_f32_e32 v16, 0xbfb8aa3b, v8
	v_pk_mul_f32 v[14:15], v[14:15], v[18:19]
	v_mul_f32_e32 v17, 0xbfb8aa3b, v9
	v_mul_f32_e32 v18, 0xbfb8aa3b, v10
	v_mul_f32_e32 v19, 0xbfb8aa3b, v11
	v_exp_f32_e32 v16, v16
	v_exp_f32_e32 v17, v17
	v_exp_f32_e32 v18, v18
	v_exp_f32_e32 v19, v19
	v_add_f32_e32 v16, 1.0, v16
	v_add_f32_e32 v17, 1.0, v17
	v_add_f32_e32 v18, 1.0, v18
	v_add_f32_e32 v19, 1.0, v19
	v_rcp_f32_e32 v16, v16
	v_rcp_f32_e32 v17, v17
	v_rcp_f32_e32 v18, v18
	v_rcp_f32_e32 v19, v19
	v_add_u32_e32 v20, 0xb0, v142
	v_pk_mul_f32 v[8:9], v[8:9], v[16:17]
	v_pk_mul_f32 v[4:5], v[4:5], v[12:13]
	v_pk_mul_f32 v[10:11], v[10:11], v[18:19]
	v_pk_mul_f32 v[0:1], v[0:1], v[146:147] op_sel_hi:[1,0]
	v_pk_mul_f32 v[2:3], v[2:3], v[146:147] op_sel_hi:[1,0]
	v_pk_mul_f32 v[6:7], v[6:7], v[146:147] op_sel_hi:[1,0]
	v_pk_mul_f32 v[10:11], v[2:3], v[10:11]
	v_pk_mul_f32 v[2:3], v[0:1], v[8:9]
	v_cvt_pk_bf16_f32 v0, v4, v5
	v_mad_i64_i32 v[4:5], s[20:21], v20, s4, v[112:113]
	v_lshl_add_u64 v[4:5], v[4:5], 0, v[114:115]
	s_mov_b64 s[26:27], -1
	s_andn2_b64 vcc, exec, s[40:41]
	v_pk_mul_f32 v[6:7], v[6:7], v[14:15]
	s_nop 0
	v_cvt_pk_bf16_f32 v1, v6, v7
	v_cvt_pk_bf16_f32 v2, v2, v3
	v_cvt_pk_bf16_f32 v3, v10, v11
	flat_store_dwordx4 v[4:5], v[0:3]
	s_cbranch_vccnz .LBB0_148
	s_andn2_b64 vcc, exec, s[44:45]
	s_cbranch_vccnz .LBB0_147
	s_barrier
	s_branch .LBB0_147

; __device__ __forceinline__ unsigned long long f2ss(float v) { return (unsigned long long)(v * 16777216.0f); }
; __device__ __forceinline__ u32x4 pack8(f32x4 v0, f32x4 v1) { u32x4 w; w.x = cvt_pk_bf16(v0[0], v0[1]); w.y = cvt_pk_bf16(v0[2], v0[3]); w.z = cvt_pk_bf16(v1[0], v1[1]); w.w = cvt_pk_bf16(v1[2], v1[3]); return w; }
;     __device__ __forceinline__ void operator()(const f32x4 (&acc)[2][2][4][2], const Unit& u, int wr, int wc, int fr, int fq, const Pre&) const {
;         const int row0 = u.pm * BM + wr * 64 + fr, col0 = u.pn * BM + wc * 32 + 8 * fq;
;         typedef __attribute__((address_space(1))) u32x4 gu32x4;
;         u32x4 bwv[2][4][2];
; #pragma unroll
;         for (int ai = 0; ai < 2; ++ai)
; #pragma unroll
;             for (int m = 0; m < 4; ++m)
; #pragma unroll
;                 for (int bj = 0; bj < 2; ++bj) bwv[ai][m][bj] = *(const gu32x4*)(hb + (size_t)(row0 + ai * HALF + m * 16) * 1024 + col0 + bj * HALF);
; #pragma unroll
;         for (int ai = 0; ai < 2; ++ai)
; #pragma unroll
;             for (int m = 0; m < 4; ++m) { const int row = row0 + ai * HALF + m * 16; const size_t off = (size_t)row * 1024 + col0; float sq = 0.f;
; #pragma unroll
;                 for (int bj = 0; bj < 2; ++bj) { const u32x4 bw = bwv[ai][m][bj];
;                     const f32x4 b0 = (f32x4){__uint_as_float(bw.x << 16), __uint_as_float(bw.x & 0xffff0000u), __uint_as_float(bw.y << 16), __uint_as_float(bw.y & 0xffff0000u)};
;                     const f32x4 b1 = (f32x4){__uint_as_float(bw.z << 16), __uint_as_float(bw.z & 0xffff0000u), __uint_as_float(bw.w << 16), __uint_as_float(bw.w & 0xffff0000u)};
;                     const f32x4 v0 = acc[ai][bj][m][0] + b0, v1 = acc[ai][bj][m][1] + b1;
;                     *(gu32x4*)(hb + off + bj * HALF) = pack8(v0, v1);
;                     sq += (v0[0] * v0[0] + v0[1] * v0[1]) + (v0[2] * v0[2] + v0[3] * v0[3]) + (v1[0] * v1[0] + v1[1] * v1[1]) + (v1[2] * v1[2] + v1[3] * v1[3]); }
;                 sq += __shfl_xor(sq, 16); sq += __shfl_xor(sq, 32); if (fq == 0) atomicAdd(ssn + row, f2ss(sq)); }
.LBB0_177:
	v_lshl_or_b32 v210, s36, 8, v241
	v_lshl_add_u32 v226, s4, 8, v145
	v_ashrrev_i32_e32 v211, 31, v210
	v_lshlrev_b64 v[228:229], 1, v[210:211]
	v_ashrrev_i32_e32 v227, 31, v226
	v_lshl_add_u64 v[112:113], s[28:29], 0, v[228:229]
	v_lshlrev_b64 v[230:231], 11, v[226:227]
	v_lshl_add_u64 v[114:115], v[112:113], 0, v[230:231]
	global_load_dwordx4 v[244:247], v[114:115], off
	global_load_dwordx4 v[192:195], v[114:115], off offset:256
	v_or_b32_e32 v114, 16, v226
	v_ashrrev_i32_e32 v115, 31, v114
	v_lshlrev_b64 v[224:225], 11, v[114:115]
	v_lshl_add_u64 v[114:115], v[112:113], 0, v[224:225]
	global_load_dwordx4 v[188:191], v[114:115], off
	global_load_dwordx4 v[184:187], v[114:115], off offset:256
	v_or_b32_e32 v114, 32, v226
	v_ashrrev_i32_e32 v115, 31, v114
	v_lshlrev_b64 v[222:223], 11, v[114:115]
	v_lshl_add_u64 v[114:115], v[112:113], 0, v[222:223]
	global_load_dwordx4 v[180:183], v[114:115], off
	global_load_dwordx4 v[176:179], v[114:115], off offset:256
	v_or_b32_e32 v114, 48, v226
	v_ashrrev_i32_e32 v115, 31, v114
	s_mov_b64 s[4:5], 0x40000
	v_lshlrev_b64 v[220:221], 11, v[114:115]
	v_lshl_add_u64 v[218:219], v[230:231], 0, s[4:5]
	s_mov_b64 s[4:5], 0x48000
	v_lshl_add_u64 v[114:115], v[112:113], 0, v[220:221]
	v_lshl_add_u64 v[216:217], v[230:231], 0, s[4:5]
	s_mov_b64 s[4:5], 0x50000
	global_load_dwordx4 v[172:175], v[114:115], off
	global_load_dwordx4 v[164:167], v[114:115], off offset:256
	v_lshl_add_u64 v[114:115], v[112:113], 0, v[218:219]
	v_lshl_add_u64 v[214:215], v[230:231], 0, s[4:5]
	s_mov_b64 s[4:5], 0x58000
	global_load_dwordx4 v[156:159], v[114:115], off
	global_load_dwordx4 v[152:155], v[114:115], off offset:256
	v_lshl_add_u64 v[114:115], v[112:113], 0, v[216:217]
	v_lshl_add_u64 v[212:213], v[230:231], 0, s[4:5]
	global_load_dwordx4 v[140:143], v[114:115], off
	global_load_dwordx4 v[136:139], v[114:115], off offset:256
	v_lshl_add_u64 v[114:115], v[112:113], 0, v[214:215]
	v_lshl_add_u64 v[112:113], v[112:113], 0, v[212:213]
	global_load_dwordx4 v[124:127], v[114:115], off
	global_load_dwordx4 v[116:119], v[114:115], off offset:256
	global_load_dwordx4 v[120:123], v[112:113], off
	s_nop 0
	global_load_dwordx4 v[112:115], v[112:113], off offset:256
	s_and_b64 vcc, exec, s[50:51]
	s_cbranch_vccz .Lalign_g2
	s_barrier
.Lalign_g2:
	v_lshl_add_u64 v[230:231], s[28:29], 0, v[230:231]
	v_lshl_add_u64 v[228:229], v[230:231], 0, v[228:229]
	s_waitcnt vmcnt(0)
	v_lshlrev_b32_e32 v248, 16, v244
	v_and_b32_e32 v249, 0xffff0000, v244
	v_lshlrev_b32_e32 v244, 16, v245
	v_and_b32_e32 v245, 0xffff0000, v245
	v_lshlrev_b32_e32 v250, 16, v246
	v_and_b32_e32 v251, 0xffff0000, v246
	v_lshlrev_b32_e32 v246, 16, v247
	v_and_b32_e32 v247, 0xffff0000, v247
	v_pk_add_f32 v[170:171], v[170:171], v[244:245]
	v_pk_add_f32 v[168:169], v[168:169], v[248:249]
	v_pk_add_f32 v[244:245], v[162:163], v[246:247]
	v_pk_add_f32 v[246:247], v[160:161], v[250:251]
	v_cvt_pk_bf16_f32 v160, v168, v169
	v_cvt_pk_bf16_f32 v161, v170, v171
	s_nop 0
	v_cvt_pk_bf16_f32 v162, v246, v247
	v_cvt_pk_bf16_f32 v163, v244, v245
	global_store_dwordx4 v[228:229], v[160:163], off
	s_nop 1
	v_mul_f32_e32 v160, v169, v169
	v_mul_f32_e32 v161, v171, v171
	v_fmac_f32_e32 v160, v168, v168
	v_fmac_f32_e32 v161, v170, v170
	v_add_f32_e32 v160, v160, v161
	v_mul_f32_e32 v161, v247, v247
	v_fmac_f32_e32 v161, v246, v246
	v_add_f32_e32 v160, v161, v160
	v_mul_f32_e32 v161, v245, v245
	v_fmac_f32_e32 v161, v244, v244
	v_add_f32_e32 v196, v161, v160
	v_lshlrev_b32_e32 v160, 16, v192
	v_and_b32_e32 v161, 0xffff0000, v192
	v_lshlrev_b32_e32 v162, 16, v193
	v_and_b32_e32 v163, 0xffff0000, v193
	v_lshlrev_b32_e32 v168, 16, v194
	v_and_b32_e32 v169, 0xffff0000, v194
	v_lshlrev_b32_e32 v170, 16, v195
	v_and_b32_e32 v171, 0xffff0000, v195
	v_pk_add_f32 v[134:135], v[134:135], v[162:163]
	v_pk_add_f32 v[132:133], v[132:133], v[160:161]
	v_pk_add_f32 v[162:163], v[128:129], v[168:169]
	v_cvt_pk_bf16_f32 v128, v132, v133
	v_cvt_pk_bf16_f32 v129, v134, v135
	v_pk_add_f32 v[160:161], v[130:131], v[170:171]
	v_cvt_pk_bf16_f32 v130, v162, v163
	s_nop 0
	v_cvt_pk_bf16_f32 v131, v160, v161
	global_store_dwordx4 v[228:229], v[128:131], off offset:256
	s_nop 1
	v_mul_f32_e32 v128, v133, v133
	v_mul_f32_e32 v129, v135, v135
	v_fmac_f32_e32 v128, v132, v132
	v_fmac_f32_e32 v129, v134, v134
	v_add_f32_e32 v128, v128, v129
	v_mul_f32_e32 v129, v163, v163
	v_fmac_f32_e32 v129, v162, v162
	v_add_f32_e32 v128, v129, v128
	v_mul_f32_e32 v129, v161, v161
	v_fmac_f32_e32 v129, v160, v160
	v_and_b32_e32 v130, 64, v236
	v_add_f32_e32 v128, v129, v128
	v_xor_b32_e32 v129, 16, v236
	v_add_u32_e32 v131, 64, v130
	v_cmp_lt_i32_e32 vcc, v129, v131
	v_add_f32_e32 v128, v196, v128
	s_nop 0
	v_cndmask_b32_e32 v129, v236, v129, vcc
	v_lshlrev_b32_e32 v130, 2, v129
	ds_bpermute_b32 v129, v130, v128
	s_waitcnt lgkmcnt(0)
	v_add_f32_e32 v132, v128, v129
	v_xor_b32_e32 v128, 32, v236
	v_cmp_lt_i32_e32 vcc, v128, v131
	s_nop 1
	v_cndmask_b32_e32 v128, v236, v128, vcc
	v_lshlrev_b32_e32 v131, 2, v128
	ds_bpermute_b32 v133, v131, v132
	v_lshl_add_u64 v[128:129], v[226:227], 3, s[48:49]
	s_and_saveexec_b64 s[26:27], s[40:41]
	s_cbranch_execz .LBB0_179
	s_waitcnt lgkmcnt(0)
	v_add_f32_e32 v132, v132, v133
	v_mul_f32_e32 v132, 0x4b800000, v132
	v_trunc_f32_e32 v132, v132
	v_mul_f32_e32 v133, 0x2f800000, v132
	v_floor_f32_e32 v133, v133
	v_fmac_f32_e32 v132, 0xcf800000, v133
	v_cvt_u32_f32_e32 v132, v132
	v_cvt_u32_f32_e32 v133, v133
	flat_atomic_add_x2 v[128:129], v[132:133]

; __device__ __forceinline__ float ss2f(unsigned long long v) { return (float)v * (1.0f / 16777216.0f); }
; __device__ __forceinline__ void rstd8(float (&r)[8], const PreSS& p, int fr) {
;     const float a = __builtin_amdgcn_rsqf(ss2f(p.v0) * (1.0f / 1024.0f) + RMS_EPS), b = __builtin_amdgcn_rsqf(ss2f(p.v1) * (1.0f / 1024.0f) + RMS_EPS);
; #pragma unroll
;     for (int k = 0; k < 8; ++k) r[k] = __shfl((k & 1) ? b : a, fr + 16 * (k >> 1));
; }
;     __device__ __forceinline__ void operator()(const f32x4 (&acc)[2][2][4][2], const Unit& u, int wr, int wc, int fr, int fq, const Pre& pre) const {
;         const int row0 = u.pm * BM + wr * 64 + fr, col0 = u.pn * BM + wc * 32 + 8 * fq;
;         float rs8[8]; rstd8(rs8, pre, fr);
;         if (u.pn == 2 || u.pn == 3) {
.LBB0_417:
	s_waitcnt vmcnt(8)
	v_ffbh_u32_e32 v154, v147
	v_min_u32_e32 v154, 32, v154
	v_lshlrev_b64 v[146:147], v154, v[146:147]
	v_min_u32_e32 v146, 1, v146
	v_or_b32_e32 v146, v147, v146
	v_ffbh_u32_e32 v147, v143
	v_min_u32_e32 v147, 32, v147
	v_cvt_f32_u32_e32 v146, v146
	v_lshlrev_b64 v[142:143], v147, v[142:143]
	v_min_u32_e32 v142, 1, v142
	v_or_b32_e32 v142, v143, v142
	v_sub_u32_e32 v154, 32, v154
	v_cvt_f32_u32_e32 v142, v142
	v_ldexp_f32 v146, v146, v154
	v_mul_f32_e32 v146, 0x33800000, v146
	v_fmamk_f32 v143, v146, 0x3a800000, v233
	v_sub_u32_e32 v146, 32, v147
	v_ldexp_f32 v142, v142, v146
	v_mul_f32_e32 v142, 0x33800000, v142
	v_fmamk_f32 v142, v142, 0x3a800000, v233
	v_rsq_f32_e32 v143, v143
	v_rsq_f32_e32 v142, v142
	v_and_or_b32 v146, v236, 64, v145
	v_lshlrev_b32_e32 v147, 2, v146
	ds_bpermute_b32 v164, v147, v143
	ds_bpermute_b32 v162, v147, v142
	ds_bpermute_b32 v160, v147, v143 offset:64
	ds_bpermute_b32 v158, v147, v142 offset:64
	ds_bpermute_b32 v156, v147, v143 offset:128
	ds_bpermute_b32 v154, v147, v142 offset:128
	ds_bpermute_b32 v146, v147, v143 offset:192
	ds_bpermute_b32 v142, v147, v142 offset:192
	s_and_b64 vcc, exec, s[20:21]
	s_cbranch_vccz .Lalign_g1e
	s_barrier
.Lalign_g1e:
	s_and_b32 s4, s68, -2
	s_cmp_eq_u32 s4, 2
	s_mov_b64 s[26:27], -1
	s_cbranch_scc1 .LBB0_419
	s_mov_b64 s[26:27], 0
